# V tile LDS layout permuted at store (ds_write2_b64) so V fragments read as one ds_read_b128, MLA and DSA attention
# baseline (speedup 1.0000x reference)
; #define A_STORE(P, buf) { *reinterpret_cast<uint4*>(ks0 + (buf) * BUF_BYTES) = P##k0; *reinterpret_cast<uint4*>(ks1 + (buf) * BUF_BYTES) = P##k1; \
;     if (NKC == 3) *reinterpret_cast<uint4*>(ks2 + (buf) * BUF_BYTES) = P##k2;                                        \
;     *reinterpret_cast<uint4*>(vs0 + (buf) * BUF_BYTES) = P##v0; *reinterpret_cast<uint4*>(vs1 + (buf) * BUF_BYTES) = P##v1; }
; template <int KS, bool MASK, int NC, bool SH>
; DI void attn_block(const u16* Qp, int qstride, const u16* Kp, int kstride, const u16* Vtp, const u64* maskp, int nkt_w, int nkt_max,
;                    const u16* gatep, int gstride, u16* outp, int ostride, char* lds, int tid) {
;     ...
;   uint4 xk0, xk1, xk2, xv0, xv1, yk0, yk1, yk2, yv0, yv1;
;   xk2 = yk2 = make_uint4(0, 0, 0, 0);
;   const int c0 = tid, c1 = tid + 256, c2 = tid + 512;
;   const u16* kg0 = Kp + (size_t)(c0 / KCH) * kstride + (c0 % KCH) * 8;
;   const u16* kg1 = Kp + (size_t)(c1 / KCH) * kstride + (c1 % KCH) * 8;
;   const u16* kg2 = Kp + (size_t)(c2 / KCH) * kstride + (c2 % KCH) * 8;
;   const u16* vg0 = Vtp + (size_t)(c0 >> 3) * S + (c0 & 7) * 8;
;   const u16* vg1 = Vtp + (size_t)(c1 >> 3) * S + (c1 & 7) * 8;
;   char* ks0 = lds + ((c0 / KCH) * KROW + (c0 % KCH) * 8) * 2;
;   char* ks1 = lds + ((c1 / KCH) * KROW + (c1 % KCH) * 8) * 2;
;   char* ks2 = lds + ((c2 / KCH) * KROW + (c2 % KCH) * 8) * 2;
;   char* vs0 = lds + K_BYTES + ((c0 >> 3) * VROW + (c0 & 7) * 8) * 2;
;   char* vs1 = lds + K_BYTES + ((c1 >> 3) * VROW + (c1 & 7) * 8) * 2;
;     ...
;   bf16x8 qf[NC][KS];
; #pragma unroll
;   for (int c = 0; c < NC; ++c)
; #pragma unroll
;     for (int ks = 0; ks < KS; ++ks) qf[c][ks] = ld8(Qp + (size_t)((SH ? 0 : 16 * c) + jn) * qstride + (SH ? 64 * c : 0) + ks * 32 + q * 8);
;   f32x4 o[4][NC]; zero_acc(o);
;   float m[NC], lsum[NC];
; #pragma unroll
;   for (int c = 0; c < NC; ++c) { m[c] = NEG_INF; lsum[c] = 0.f; }
;     ...
;   A_LOAD(x, 0);
;   { const int t1 = (nkt_max > 1) ? 1 : 0; A_LOAD(y, t1); }
;   A_STORE(x, 0);
;   __syncthreads();
.LBB0_805:
	s_mul_i32 s4, s0, 0x1400000
	v_add_u32_e32 v9, 0x100, v163
	v_ashrrev_i32_e32 v2, 31, v163
	s_mul_hi_i32 s5, s0, 0x1400000
	s_add_u32 s12, s76, s4
	v_lshrrev_b32_e32 v2, 29, v2
	v_ashrrev_i32_e32 v4, 31, v9
	s_addc_u32 s13, s77, s5
	s_lshl_b64 s[14:15], s[0:1], 19
	v_readlane_b32 s7, v249, 63
	v_add_u32_e32 v2, v163, v2
	v_lshrrev_b32_e32 v4, 29, v4
	s_add_u32 s14, s7, s14
	v_readlane_b32 s7, v250, 0
	v_ashrrev_i32_e32 v7, 3, v2
	v_and_b32_e32 v2, 0x1ffffff8, v2
	v_add_u32_e32 v4, v9, v4
	s_addc_u32 s15, s7, s15
	v_sub_u32_e32 v2, v163, v2
	v_ashrrev_i32_e32 v8, 3, v4
	v_and_b32_e32 v4, 0x1ffffff8, v4
	s_waitcnt vmcnt(22)
	v_ashrrev_i32_e32 v34, 3, v163
	s_movk_i32 s7, 0x48
	v_lshlrev_b32_e32 v2, 3, v2
	v_sub_u32_e32 v4, v9, v4
	v_ashrrev_i32_e32 v35, 31, v34
	s_waitcnt vmcnt(21)
	v_ashrrev_i32_e32 v38, 3, v9
	v_mul_lo_u32 v9, v7, s7
	v_lshlrev_b32_e32 v4, 3, v4
	v_lshlrev_b64 v[36:37], 13, v[34:35]
	v_lshlrev_b32_e32 v35, 3, v163
	v_add_lshl_u32 v164, v9, v2, 1
	v_mul_lo_u32 v9, v8, s7
	s_waitcnt vmcnt(16)
	v_and_b32_e32 v42, 56, v35
	v_add_lshl_u32 v165, v9, v4, 1
	v_mul_lo_u32 v9, v34, s7
	v_ashrrev_i32_e32 v39, 31, v38
	v_add_lshl_u32 v172, v9, v42, 1
	v_mul_lo_u32 v9, v38, s7
	v_mov_b64_e32 v[34:35], s[12:13]
	s_movk_i32 s7, 0x1400
	v_ashrrev_i32_e32 v3, 31, v2
	v_ashrrev_i32_e32 v5, 31, v4
	v_lshlrev_b64 v[40:41], 13, v[38:39]
	v_add_lshl_u32 v173, v9, v42, 1
	v_and_b32_e32 v246, 1, v130
	v_lshlrev_b32_e32 v246, 4, v246
	v_bfe_u32 v247, v130, 1, 1
	v_mul_u32_u24_e32 v247, 24, v247
	v_sub_u32_e32 v246, v246, v247
	v_add_u32_e32 v242, v172, v246
	v_add_u32_e32 v243, 0x6c00, v242
	v_add_u32_e32 v242, 0x2400, v242
	v_add_u32_e32 v244, v173, v246
	v_add_u32_e32 v245, 0x6c00, v244
	v_add_u32_e32 v244, 0x2400, v244
	v_mad_i64_i32 v[38:39], s[12:13], v7, s7, v[34:35]
	v_mad_i64_i32 v[34:35], s[12:13], v8, s7, v[34:35]
	v_lshl_add_u64 v[36:37], s[14:15], 0, v[36:37]
	v_lshlrev_b32_e32 v42, 1, v42
	v_mov_b32_e32 v43, v1
	v_lshl_add_u64 v[40:41], s[14:15], 0, v[40:41]
	v_lshl_add_u64 v[120:121], v[36:37], 0, v[42:43]
	v_lshl_add_u64 v[36:37], v[2:3], 1, v[38:39]
	v_lshl_add_u64 v[34:35], v[4:5], 1, v[34:35]
	s_lshl_b32 s34, s8, 1
	v_lshl_add_u64 v[122:123], v[40:41], 0, v[42:43]
	global_load_dwordx4 v[42:45], v[36:37], off offset:768
	global_load_dwordx4 v[50:53], v[34:35], off offset:768
	global_load_dwordx4 v[54:57], v[120:121], off
	global_load_dwordx4 v[62:65], v[122:123], off
	v_lshl_add_u64 v[36:37], v[36:37], 0, s[34:35]
	v_lshl_add_u64 v[34:35], v[34:35], 0, s[34:35]
	s_lshl_b32 s34, s6, 1
	global_load_dwordx4 v[58:61], v[34:35], off offset:768
	v_lshl_add_u64 v[34:35], v[120:121], 0, s[34:35]
	global_load_dwordx4 v[46:49], v[36:37], off offset:768
	global_load_dwordx4 v[66:69], v[34:35], off
	v_lshl_add_u64 v[34:35], v[122:123], 0, s[34:35]
	global_load_dwordx4 v[70:73], v[34:35], off
	s_mov_b64 s[6:7], -1
	s_cmpk_lt_i32 s11, 0x800
	v_lshlrev_b32_e32 v124, 2, v6
	s_waitcnt vmcnt(7)
	ds_write_b128 v164, v[42:45]
	s_waitcnt vmcnt(6)
	ds_write_b128 v165, v[50:53]
	s_waitcnt vmcnt(5)
	ds_write2_b64 v242, v[54:55], v[56:57] offset1:2
	s_waitcnt vmcnt(4)
	ds_write2_b64 v244, v[62:63], v[64:65] offset1:2
	s_waitcnt lgkmcnt(0)
	s_barrier
	s_cbranch_scc1 .LBB0_807
	v_mov_b32_e32 v125, v1
	s_mov_b64 s[6:7], 0
.LBB0_807:
	s_andn2_b64 vcc, exec, s[6:7]
	s_cbranch_vccnz .LBB0_828
	s_movk_i32 s8, 0x1400
	s_sub_i32 s57, 0, s10
	v_mad_i64_i32 v[34:35], s[6:7], v7, s8, 0
	v_mad_i64_i32 v[8:9], s[6:7], v8, s8, 0
	v_mul_u32_u24_e32 v7, 0x90, v162
	v_lshlrev_b32_e32 v36, 3, v6
	s_add_i32 s55, s57, 64
	v_lshl_add_u32 v174, v6, 4, v7
	s_add_i32 s56, s57, 63
	s_add_i32 s57, s57, 61
	s_lshl_b64 s[0:1], s[0:1], 21
	s_lshl_b64 s[2:3], s[2:3], 9
	v_lshl_add_u64 v[6:7], s[4:5], 0, v[8:9]
	s_add_u32 s0, s0, s2
	v_lshl_add_u64 v[128:129], v[4:5], 1, v[6:7]
	v_lshl_add_u64 v[4:5], s[4:5], 0, v[34:35]
	s_addc_u32 s1, s1, s3
	v_lshl_add_u64 v[134:135], v[2:3], 1, v[4:5]
	v_mov_b32_e32 v4, v1
	v_mov_b32_e32 v5, v1
	v_mov_b32_e32 v175, v174
	v_lshl_add_u64 v[126:127], s[0:1], 0, v[0:1]
	v_mov_b32_e32 v0, v1
	v_mov_b32_e32 v2, v1
	v_mov_b32_e32 v3, v1
	v_mov_b64_e32 v[76:77], v[4:5]
	v_mov_b64_e32 v[92:93], v[4:5]
	v_mov_b64_e32 v[8:9], v[4:5]
	v_mov_b64_e32 v[80:81], v[4:5]
	v_mov_b64_e32 v[96:97], v[4:5]
	v_mov_b64_e32 v[36:37], v[4:5]
	v_mov_b64_e32 v[84:85], v[4:5]
	v_mov_b64_e32 v[100:101], v[4:5]
	v_mov_b64_e32 v[40:41], v[4:5]
	v_mov_b64_e32 v[88:89], v[4:5]
	v_mov_b64_e32 v[104:105], v[4:5]
	v_mov_b32_e32 v125, v1
	s_mov_b32 s59, 0
	v_mov_b64_e32 v[136:137], 0
	v_mov_b32_e32 v110, 0
	v_mov_b32_e32 v156, 0xff800000
	s_movk_i32 s46, 0xc0
	v_mov_b64_e32 v[74:75], v[2:3]
	v_mov_b64_e32 v[90:91], v[2:3]
	v_mov_b64_e32 v[6:7], v[2:3]
	v_mov_b64_e32 v[78:79], v[2:3]
	v_mov_b64_e32 v[94:95], v[2:3]
	v_mov_b64_e32 v[34:35], v[2:3]
	v_mov_b64_e32 v[82:83], v[2:3]
	v_mov_b64_e32 v[98:99], v[2:3]
	v_mov_b64_e32 v[38:39], v[2:3]
	v_mov_b64_e32 v[86:87], v[2:3]
	v_mov_b64_e32 v[102:103], v[2:3]
	v_mov_b32_e32 v158, 0xff800000
	v_mov_b32_e32 v157, 0xff800000
	v_mov_b64_e32 v[138:139], 0
	v_mov_b64_e32 v[118:119], v[0:1]
	v_readlane_b32 s34, v251, 6

; DI unsigned pack2(float a, float b) { return __builtin_bit_cast(unsigned, __builtin_convertvector((f32x2_t){a, b}, bf16x2_t)); }
; DI float fexp2(float x) { return __builtin_amdgcn_exp2f(x); }
; template <int KS, bool MASK, int NC, bool SH>
; DI void attn_block(const u16* Qp, int qstride, const u16* Kp, int kstride, const u16* Vtp, const u64* maskp, int nkt_w, int nkt_max,
;                    const u16* gatep, int gstride, u16* outp, int ostride, char* lds, int tid) {
;     ...
;       float ps = 0.f;
; #pragma unroll
;       for (int a = 0; a < 4; ++a)
; #pragma unroll
;         for (int r = 0; r < 4; ++r) { float p = fexp2(s[a][c][r] - mu); s[a][c][r] = p; ps += p; }
;       lsum[c] = lsum[c] * alpha[c] + ps;
;     }
;     bool resc = false;
; #pragma unroll
;     for (int c = 0; c < NC; ++c) resc = resc || (alpha[c] != 1.0f);
;     if (__builtin_amdgcn_ballot_w64(resc) != 0ull) {
; #pragma unroll
;       for (int c = 0; c < NC; ++c)
; #pragma unroll
;         for (int dt = 0; dt < 4; ++dt)
; #pragma unroll
;           for (int r = 0; r < 4; ++r) o[dt][c][r] *= alpha[c];
;     }
; #pragma unroll
;     for (int kk = 0; kk < 2; ++kk) {
;       bf16x8 pf[NC];
; #pragma unroll
;       for (int c = 0; c < NC; ++c) {
;         uint4 w; w.x = pack2(s[2 * kk][c][0], s[2 * kk][c][1]); w.y = pack2(s[2 * kk][c][2], s[2 * kk][c][3]);
;         w.z = pack2(s[2 * kk + 1][c][0], s[2 * kk + 1][c][1]); w.w = pack2(s[2 * kk + 1][c][2], s[2 * kk + 1][c][3]);
;         pf[c] = __builtin_bit_cast(bf16x8, w);
;       }
.LBB0_816:
	v_sub_f32_e32 v153, v153, v207
	v_exp_f32_e32 v168, v153
	v_sub_f32_e32 v156, v180, v207
	v_exp_f32_e32 v169, v156
	v_sub_f32_e32 v156, v179, v207
	v_exp_f32_e32 v212, v156
	v_sub_f32_e32 v149, v149, v207
	v_exp_f32_e32 v213, v149
	v_add_f32_e32 v153, 0, v168
	v_add_f32_e32 v153, v169, v153
	v_add_f32_e32 v153, v212, v153
	v_add_f32_e32 v149, v213, v153
	v_sub_f32_e32 v153, v154, v207
	v_exp_f32_e32 v214, v153
	v_sub_f32_e32 v147, v147, v207
	v_exp_f32_e32 v215, v147
	v_add_f32_e32 v149, v214, v149
	v_add_f32_e32 v147, v215, v149
	v_sub_f32_e32 v149, v151, v207
	v_exp_f32_e32 v216, v149
	v_sub_f32_e32 v149, v155, v207
	v_exp_f32_e32 v217, v149
	v_sub_f32_e32 v149, v181, v207
	v_exp_f32_e32 v180, v149
	v_sub_f32_e32 v149, v159, v207
	v_exp_f32_e32 v181, v149
	v_sub_f32_e32 v149, v182, v207
	v_add_f32_e32 v147, v216, v147
	v_exp_f32_e32 v182, v149
	v_sub_f32_e32 v149, v183, v207
	v_add_f32_e32 v147, v217, v147
	v_exp_f32_e32 v183, v149
	v_sub_f32_e32 v149, v184, v207
	v_add_f32_e32 v147, v180, v147
	v_exp_f32_e32 v184, v149
	v_sub_f32_e32 v149, v202, v207
	v_add_f32_e32 v147, v181, v147
	v_exp_f32_e32 v218, v149
	v_sub_f32_e32 v149, v203, v207
	v_add_f32_e32 v147, v182, v147
	v_exp_f32_e32 v219, v149
	v_sub_f32_e32 v149, v204, v207
	v_add_f32_e32 v147, v183, v147
	v_exp_f32_e32 v204, v149
	v_add_f32_e32 v147, v184, v147
	v_add_f32_e32 v147, v218, v147
	v_add_f32_e32 v147, v219, v147
	v_add_f32_e32 v179, v204, v147
	v_fmac_f32_e32 v179, v110, v0
	v_sub_f32_e32 v0, v200, v206
	v_exp_f32_e32 v203, v0
	v_sub_f32_e32 v0, v201, v206
	v_exp_f32_e32 v201, v0
	v_sub_f32_e32 v0, v199, v206
	v_exp_f32_e32 v199, v0
	v_sub_f32_e32 v0, v197, v206
	v_exp_f32_e32 v197, v0
	v_sub_f32_e32 v0, v198, v206
	v_exp_f32_e32 v207, v0
	v_sub_f32_e32 v0, v196, v206
	v_exp_f32_e32 v209, v0
	v_sub_f32_e32 v0, v195, v206
	v_exp_f32_e32 v195, v0
	v_sub_f32_e32 v0, v193, v206
	v_exp_f32_e32 v211, v0
	v_sub_f32_e32 v0, v194, v206
	v_exp_f32_e32 v147, v0
	v_sub_f32_e32 v0, v191, v206
	v_exp_f32_e32 v149, v0
	v_sub_f32_e32 v0, v189, v206
	v_exp_f32_e32 v151, v0
	v_sub_f32_e32 v0, v186, v206
	v_exp_f32_e32 v153, v0
	v_sub_f32_e32 v0, v187, v206
	v_exp_f32_e32 v155, v0
	v_sub_f32_e32 v0, v185, v206
	v_exp_f32_e32 v157, v0
	v_sub_f32_e32 v0, v161, v206
	v_exp_f32_e32 v159, v0
	v_sub_f32_e32 v0, v160, v206
	v_exp_f32_e32 v161, v0
	v_sub_f32_e32 v0, v152, v205
	v_exp_f32_e32 v202, v0
	v_sub_f32_e32 v0, v150, v205
	v_exp_f32_e32 v200, v0
	v_sub_f32_e32 v0, v148, v205
	v_exp_f32_e32 v198, v0
	v_sub_f32_e32 v0, v117, v205
	v_exp_f32_e32 v196, v0
	v_sub_f32_e32 v0, v146, v205
	v_exp_f32_e32 v206, v0
	v_sub_f32_e32 v0, v116, v205
	v_exp_f32_e32 v208, v0
	v_sub_f32_e32 v0, v115, v205
	v_exp_f32_e32 v194, v0
	v_sub_f32_e32 v0, v113, v205
	v_exp_f32_e32 v210, v0
	v_sub_f32_e32 v0, v114, v205
	v_exp_f32_e32 v146, v0
	v_sub_f32_e32 v0, v112, v205
	v_pk_add_f32 v[112:113], v[202:203], 0 op_sel_hi:[1,0]
	v_exp_f32_e32 v148, v0
	v_pk_add_f32 v[112:113], v[200:201], v[112:113]
	v_sub_f32_e32 v0, v111, v205
	v_pk_add_f32 v[112:113], v[198:199], v[112:113]
	v_exp_f32_e32 v150, v0
	v_sub_f32_e32 v0, v108, v205
	v_pk_add_f32 v[112:113], v[196:197], v[112:113]
	v_exp_f32_e32 v152, v0
	v_sub_f32_e32 v0, v109, v205
	v_pk_add_f32 v[112:113], v[206:207], v[112:113]
	v_exp_f32_e32 v154, v0
	v_sub_f32_e32 v0, v192, v205
	v_pk_add_f32 v[112:113], v[208:209], v[112:113]
	v_exp_f32_e32 v156, v0
	v_sub_f32_e32 v0, v190, v205
	v_pk_add_f32 v[112:113], v[194:195], v[112:113]
	v_exp_f32_e32 v158, v0
	v_sub_f32_e32 v0, v188, v205
	v_pk_add_f32 v[112:113], v[210:211], v[112:113]
	v_exp_f32_e32 v160, v0
	v_add_u32_e32 v0, 0x2000, v175
	v_pk_add_f32 v[112:113], v[146:147], v[112:113]
	ds_read_b128 v[186:189], v0 offset:1024
	v_pk_add_f32 v[112:113], v[148:149], v[112:113]
	v_cvt_pk_bf16_f32 v114, v168, v169
	v_pk_add_f32 v[108:109], v[150:151], v[112:113]
	v_cvt_pk_bf16_f32 v115, v212, v213
	v_pk_add_f32 v[108:109], v[152:153], v[108:109]
	v_cvt_pk_bf16_f32 v116, v214, v215
	v_pk_add_f32 v[108:109], v[154:155], v[108:109]
	v_cvt_pk_bf16_f32 v117, v216, v217
	v_pk_add_f32 v[108:109], v[156:157], v[108:109]
	v_cvt_pk_bf16_f32 v110, v202, v200
	v_pk_add_f32 v[108:109], v[158:159], v[108:109]
	v_cvt_pk_bf16_f32 v111, v198, v196
	v_pk_add_f32 v[108:109], v[160:161], v[108:109]
	v_cvt_pk_bf16_f32 v112, v206, v208
	v_pk_fma_f32 v[118:119], v[118:119], v[106:107], v[108:109]
	v_cvt_pk_bf16_f32 v106, v203, v201
	v_cvt_pk_bf16_f32 v107, v199, v197
	v_cvt_pk_bf16_f32 v108, v207, v209
	v_cvt_pk_bf16_f32 v109, v195, v211
	v_cvt_pk_bf16_f32 v113, v194, v210
	v_add_u32_e32 v168, 0x2800, v175
	s_waitcnt lgkmcnt(0)
; DI f32x4 mfma16(bf16x8 a, bf16x8 b, f32x4 c) { return __builtin_amdgcn_mfma_f32_16x16x32_bf16(a, b, c, 0, 0, 0); }
; template <int KS, bool MASK, int NC, bool SH>
; DI void attn_block(const u16* Qp, int qstride, const u16* Kp, int kstride, const u16* Vtp, const u64* maskp, int nkt_w, int nkt_max,
;                    const u16* gatep, int gstride, u16* outp, int ostride, char* lds, int tid) {
;     ...
; #pragma unroll
;       for (int dt = 0; dt < 4; ++dt) {
;         const char* vp = vb + ((16 * dt + jn) * VROW + kk * 32 + 4 * q) * 2;
;         const uint2 lo = *reinterpret_cast<const uint2*>(vp), hi = *reinterpret_cast<const uint2*>(vp + 32);
;         uint4 w; w.x = lo.x; w.y = lo.y; w.z = hi.x; w.w = hi.y;
;         const bf16x8 vf = __builtin_bit_cast(bf16x8, w);
; #pragma unroll
;         for (int c = 0; c < NC; ++c) o[dt][c] = mfma16(vf, pf[c], o[dt][c]);
;       }
;     }
	v_mfma_f32_16x16x32_bf16 v[102:105], v[186:189], v[114:117], v[102:105]
	v_add_u32_e32 v169, 0x3000, v175
	v_add_u32_e32 v185, 0x3800, v175
	v_mfma_f32_16x16x32_bf16 v[86:89], v[186:189], v[106:109], v[86:89]
	v_mfma_f32_16x16x32_bf16 v[38:41], v[186:189], v[110:113], v[38:41]
	ds_read_b128 v[186:189], v168 offset:1280
	s_waitcnt lgkmcnt(0)
	v_mfma_f32_16x16x32_bf16 v[98:101], v[186:189], v[114:117], v[98:101]
	v_mfma_f32_16x16x32_bf16 v[82:85], v[186:189], v[106:109], v[82:85]
	v_mfma_f32_16x16x32_bf16 v[34:37], v[186:189], v[110:113], v[34:37]
	ds_read_b128 v[186:189], v169 offset:1536
	s_waitcnt lgkmcnt(0)
	v_mfma_f32_16x16x32_bf16 v[94:97], v[186:189], v[114:117], v[94:97]
	v_mfma_f32_16x16x32_bf16 v[78:81], v[186:189], v[106:109], v[78:81]
	v_mfma_f32_16x16x32_bf16 v[6:9], v[186:189], v[110:113], v[6:9]
	ds_read_b128 v[186:189], v185 offset:1792
	s_waitcnt lgkmcnt(0)
	v_mfma_f32_16x16x32_bf16 v[90:93], v[186:189], v[114:117], v[90:93]
	v_cvt_pk_bf16_f32 v114, v147, v149
	v_cvt_pk_bf16_f32 v115, v151, v153
	v_cvt_pk_bf16_f32 v116, v155, v157
	v_mfma_f32_16x16x32_bf16 v[74:77], v[186:189], v[106:109], v[74:77]
	v_cvt_pk_bf16_f32 v106, v146, v148
	ds_read_b128 v[146:149], v0 offset:1088
	v_cvt_pk_bf16_f32 v117, v159, v161
	v_mfma_f32_16x16x32_bf16 v[2:5], v[186:189], v[110:113], v[2:5]
	v_cvt_pk_bf16_f32 v110, v180, v181
	v_cvt_pk_bf16_f32 v111, v182, v183
	v_cvt_pk_bf16_f32 v112, v184, v218
	v_cvt_pk_bf16_f32 v113, v219, v204
	v_cvt_pk_bf16_f32 v107, v150, v152
	v_cvt_pk_bf16_f32 v108, v154, v156
	v_cvt_pk_bf16_f32 v109, v158, v160
	s_waitcnt lgkmcnt(0)
	v_mfma_f32_16x16x32_bf16 v[102:105], v[146:149], v[110:113], v[102:105]
	v_mfma_f32_16x16x32_bf16 v[86:89], v[146:149], v[114:117], v[86:89]
	v_mfma_f32_16x16x32_bf16 v[38:41], v[146:149], v[106:109], v[38:41]
	ds_read_b128 v[146:149], v168 offset:1344
	s_waitcnt lgkmcnt(0)
	v_mfma_f32_16x16x32_bf16 v[98:101], v[146:149], v[110:113], v[98:101]
	v_mfma_f32_16x16x32_bf16 v[82:85], v[146:149], v[114:117], v[82:85]
	v_mfma_f32_16x16x32_bf16 v[34:37], v[146:149], v[106:109], v[34:37]
	ds_read_b128 v[146:149], v169 offset:1600
	s_waitcnt lgkmcnt(0)
	v_mfma_f32_16x16x32_bf16 v[94:97], v[146:149], v[110:113], v[94:97]
	v_mfma_f32_16x16x32_bf16 v[78:81], v[146:149], v[114:117], v[78:81]
	v_mfma_f32_16x16x32_bf16 v[6:9], v[146:149], v[106:109], v[6:9]
	ds_read_b128 v[146:149], v185 offset:1856
	s_waitcnt lgkmcnt(0)
	v_mfma_f32_16x16x32_bf16 v[90:93], v[146:149], v[110:113], v[90:93]
	v_mov_b32_e32 v110, v179
	v_mfma_f32_16x16x32_bf16 v[74:77], v[146:149], v[114:117], v[74:77]
	v_mfma_f32_16x16x32_bf16 v[2:5], v[146:149], v[106:109], v[2:5]
	s_branch .LBB0_818

; #define A_STORE(P, buf) { *reinterpret_cast<uint4*>(ks0 + (buf) * BUF_BYTES) = P##k0; *reinterpret_cast<uint4*>(ks1 + (buf) * BUF_BYTES) = P##k1; \
;     if (NKC == 3) *reinterpret_cast<uint4*>(ks2 + (buf) * BUF_BYTES) = P##k2;                                        \
;     *reinterpret_cast<uint4*>(vs0 + (buf) * BUF_BYTES) = P##v0; *reinterpret_cast<uint4*>(vs1 + (buf) * BUF_BYTES) = P##v1; }
; template <int KS, bool MASK, int NC, bool SH>
; DI void attn_block(const u16* Qp, int qstride, const u16* Kp, int kstride, const u16* Vtp, const u64* maskp, int nkt_w, int nkt_max,
;                    const u16* gatep, int gstride, u16* outp, int ostride, char* lds, int tid) {
;     ...
;     A_STORE(y, 1);
;     __syncthreads();
;     if (kt + 3 < nkt_max) A_LOAD(y, kt + 3);
.LBB0_818:
	s_add_i32 s0, s59, 3
	s_cmp_ge_i32 s0, s55
	s_waitcnt vmcnt(2)
	ds_write_b128 v164, v[46:49] offset:18432
	ds_write_b128 v165, v[58:61] offset:18432
	s_waitcnt vmcnt(1)
	ds_write2_b64 v243, v[66:67], v[68:69] offset1:2
	s_waitcnt vmcnt(0)
	ds_write2_b64 v245, v[70:71], v[72:73] offset1:2
	s_waitcnt lgkmcnt(0)
	s_barrier
	s_cbranch_scc1 .LBB0_820
	v_add_co_u32_e32 v46, vcc, 0xc580000, v144
	s_mov_b32 s47, s35
	s_nop 0
	v_addc_co_u32_e32 v47, vcc, 0, v145, vcc
	v_add_co_u32_e32 v58, vcc, 0xc580000, v142
	s_lshl_b64 s[0:1], s[46:47], 1
	s_nop 0
	v_addc_co_u32_e32 v59, vcc, 0, v143, vcc
	v_lshl_add_u64 v[66:67], v[120:121], 0, s[0:1]
	v_lshl_add_u64 v[70:71], v[122:123], 0, s[0:1]
	global_load_dwordx4 v[46:49], v[46:47], off offset:768
	s_nop 0
	global_load_dwordx4 v[58:61], v[58:59], off offset:768
	s_nop 0
	global_load_dwordx4 v[66:69], v[66:67], off
	s_nop 0
	global_load_dwordx4 v[70:73], v[70:71], off

; DI unsigned pack2(float a, float b) { return __builtin_bit_cast(unsigned, __builtin_convertvector((f32x2_t){a, b}, bf16x2_t)); }
; DI float fexp2(float x) { return __builtin_amdgcn_exp2f(x); }
; template <int KS, bool MASK, int NC, bool SH>
; DI void attn_block(const u16* Qp, int qstride, const u16* Kp, int kstride, const u16* Vtp, const u64* maskp, int nkt_w, int nkt_max,
;                    const u16* gatep, int gstride, u16* outp, int ostride, char* lds, int tid) {
;     ...
;       float ps = 0.f;
; #pragma unroll
;       for (int a = 0; a < 4; ++a)
; #pragma unroll
;         for (int r = 0; r < 4; ++r) { float p = fexp2(s[a][c][r] - mu); s[a][c][r] = p; ps += p; }
;       lsum[c] = lsum[c] * alpha[c] + ps;
;     }
;     bool resc = false;
; #pragma unroll
;     for (int c = 0; c < NC; ++c) resc = resc || (alpha[c] != 1.0f);
;     if (__builtin_amdgcn_ballot_w64(resc) != 0ull) {
; #pragma unroll
;       for (int c = 0; c < NC; ++c)
; #pragma unroll
;         for (int dt = 0; dt < 4; ++dt)
; #pragma unroll
;           for (int r = 0; r < 4; ++r) o[dt][c][r] *= alpha[c];
;     }
; #pragma unroll
;     for (int kk = 0; kk < 2; ++kk) {
;       bf16x8 pf[NC];
; #pragma unroll
;       for (int c = 0; c < NC; ++c) {
;         uint4 w; w.x = pack2(s[2 * kk][c][0], s[2 * kk][c][1]); w.y = pack2(s[2 * kk][c][2], s[2 * kk][c][3]);
;         w.z = pack2(s[2 * kk + 1][c][0], s[2 * kk + 1][c][1]); w.w = pack2(s[2 * kk + 1][c][2], s[2 * kk + 1][c][3]);
;         pf[c] = __builtin_bit_cast(bf16x8, w);
;       }
.LBB0_823:
	v_sub_f32_e32 v147, v147, v201
	v_exp_f32_e32 v168, v147
	v_sub_f32_e32 v160, v160, v201
	v_exp_f32_e32 v169, v160
	v_sub_f32_e32 v159, v159, v201
	v_exp_f32_e32 v202, v159
	v_sub_f32_e32 v143, v143, v201
	v_exp_f32_e32 v203, v143
	v_add_f32_e32 v147, 0, v168
	v_add_f32_e32 v147, v169, v147
	v_add_f32_e32 v147, v202, v147
	v_add_f32_e32 v143, v203, v147
	v_sub_f32_e32 v147, v149, v201
	v_exp_f32_e32 v204, v147
	v_sub_f32_e32 v141, v141, v201
	v_exp_f32_e32 v205, v141
	v_add_f32_e32 v143, v204, v143
	v_add_f32_e32 v141, v205, v143
	v_sub_f32_e32 v143, v145, v201
	v_exp_f32_e32 v206, v143
	v_sub_f32_e32 v143, v151, v201
	v_exp_f32_e32 v207, v143
	v_sub_f32_e32 v143, v161, v201
	v_exp_f32_e32 v160, v143
	v_sub_f32_e32 v143, v153, v201
	v_exp_f32_e32 v161, v143
	v_sub_f32_e32 v143, v182, v201
	v_add_f32_e32 v141, v206, v141
	v_exp_f32_e32 v176, v143
	v_sub_f32_e32 v143, v186, v201
	v_add_f32_e32 v141, v207, v141
	v_exp_f32_e32 v177, v143
	v_sub_f32_e32 v143, v196, v201
	v_add_f32_e32 v141, v160, v141
	v_exp_f32_e32 v178, v143
	v_sub_f32_e32 v143, v197, v201
	v_add_f32_e32 v141, v161, v141
	v_exp_f32_e32 v208, v143
	v_sub_f32_e32 v143, v198, v201
	v_add_f32_e32 v141, v176, v141
	v_exp_f32_e32 v209, v143
	v_sub_f32_e32 v143, v199, v201
	v_add_f32_e32 v141, v177, v141
	v_exp_f32_e32 v210, v143
	v_add_f32_e32 v141, v178, v141
	v_add_f32_e32 v141, v208, v141
	v_add_f32_e32 v141, v209, v141
	v_add_f32_e32 v159, v210, v141
	v_fmac_f32_e32 v159, v110, v0
	v_sub_f32_e32 v0, v194, v200
	v_exp_f32_e32 v197, v0
	v_sub_f32_e32 v0, v195, v200
	v_exp_f32_e32 v195, v0
	v_sub_f32_e32 v0, v193, v200
	v_exp_f32_e32 v193, v0
	v_sub_f32_e32 v0, v191, v200
	v_exp_f32_e32 v191, v0
	v_sub_f32_e32 v0, v192, v200
	v_exp_f32_e32 v199, v0
	v_sub_f32_e32 v0, v190, v200
	v_exp_f32_e32 v201, v0
	v_sub_f32_e32 v0, v189, v200
	v_exp_f32_e32 v189, v0
	v_sub_f32_e32 v0, v187, v200
	v_exp_f32_e32 v187, v0
	v_sub_f32_e32 v0, v188, v200
	v_exp_f32_e32 v141, v0
	v_sub_f32_e32 v0, v185, v200
	v_exp_f32_e32 v143, v0
	v_sub_f32_e32 v0, v183, v200
	v_exp_f32_e32 v145, v0
	v_sub_f32_e32 v0, v180, v200
	v_exp_f32_e32 v147, v0
	v_sub_f32_e32 v0, v181, v200
	v_exp_f32_e32 v149, v0
	v_sub_f32_e32 v0, v179, v200
	v_exp_f32_e32 v151, v0
	v_sub_f32_e32 v0, v155, v200
	v_exp_f32_e32 v153, v0
	v_sub_f32_e32 v0, v154, v200
	v_exp_f32_e32 v155, v0
	v_sub_f32_e32 v0, v152, v184
	v_exp_f32_e32 v196, v0
	v_sub_f32_e32 v0, v150, v184
	v_exp_f32_e32 v194, v0
	v_sub_f32_e32 v0, v148, v184
	v_exp_f32_e32 v192, v0
	v_sub_f32_e32 v0, v144, v184
	v_exp_f32_e32 v190, v0
	v_sub_f32_e32 v0, v146, v184
	v_exp_f32_e32 v198, v0
	v_sub_f32_e32 v0, v142, v184
	v_exp_f32_e32 v200, v0
	v_sub_f32_e32 v0, v140, v184
	v_exp_f32_e32 v188, v0
	v_sub_f32_e32 v0, v113, v184
	v_exp_f32_e32 v186, v0
	v_sub_f32_e32 v0, v114, v184
	v_pk_add_f32 v[180:181], v[196:197], 0 op_sel_hi:[1,0]
	v_exp_f32_e32 v140, v0
	v_sub_f32_e32 v0, v112, v184
	v_pk_add_f32 v[180:181], v[194:195], v[180:181]
	v_exp_f32_e32 v142, v0
	v_sub_f32_e32 v0, v111, v184
	v_pk_add_f32 v[180:181], v[192:193], v[180:181]
	v_exp_f32_e32 v144, v0
	v_sub_f32_e32 v0, v108, v184
	v_pk_add_f32 v[180:181], v[190:191], v[180:181]
	v_exp_f32_e32 v146, v0
	v_sub_f32_e32 v0, v109, v184
	v_pk_add_f32 v[180:181], v[198:199], v[180:181]
	v_exp_f32_e32 v148, v0
	v_sub_f32_e32 v0, v117, v184
	v_pk_add_f32 v[180:181], v[200:201], v[180:181]
	v_exp_f32_e32 v150, v0
	v_sub_f32_e32 v0, v116, v184
	v_pk_add_f32 v[180:181], v[188:189], v[180:181]
	v_exp_f32_e32 v152, v0
	v_sub_f32_e32 v0, v115, v184
	v_exp_f32_e32 v154, v0
	v_pk_add_f32 v[108:109], v[186:187], v[180:181]
	v_add_u32_e32 v0, 0x6800, v175
	v_pk_add_f32 v[108:109], v[140:141], v[108:109]
	ds_read_b128 v[180:183], v0 offset:1024
	v_pk_add_f32 v[108:109], v[142:143], v[108:109]
	v_cvt_pk_bf16_f32 v114, v168, v169
	v_pk_add_f32 v[108:109], v[144:145], v[108:109]
	v_cvt_pk_bf16_f32 v115, v202, v203
	v_pk_add_f32 v[108:109], v[146:147], v[108:109]
	v_cvt_pk_bf16_f32 v116, v204, v205
	v_pk_add_f32 v[108:109], v[148:149], v[108:109]
	v_cvt_pk_bf16_f32 v117, v206, v207
	v_pk_add_f32 v[108:109], v[150:151], v[108:109]
	v_cvt_pk_bf16_f32 v110, v196, v194
	v_pk_add_f32 v[108:109], v[152:153], v[108:109]
	v_cvt_pk_bf16_f32 v111, v192, v190
	v_pk_add_f32 v[108:109], v[154:155], v[108:109]
	v_cvt_pk_bf16_f32 v112, v198, v200
	v_pk_fma_f32 v[118:119], v[118:119], v[106:107], v[108:109]
	v_cvt_pk_bf16_f32 v106, v197, v195
	v_cvt_pk_bf16_f32 v107, v193, v191
	v_cvt_pk_bf16_f32 v108, v199, v201
	v_cvt_pk_bf16_f32 v109, v189, v187
	v_cvt_pk_bf16_f32 v113, v188, v186
	v_add_u32_e32 v168, 0x7000, v175
	s_waitcnt lgkmcnt(0)
; DI f32x4 mfma16(bf16x8 a, bf16x8 b, f32x4 c) { return __builtin_amdgcn_mfma_f32_16x16x32_bf16(a, b, c, 0, 0, 0); }
; template <int KS, bool MASK, int NC, bool SH>
; DI void attn_block(const u16* Qp, int qstride, const u16* Kp, int kstride, const u16* Vtp, const u64* maskp, int nkt_w, int nkt_max,
;                    const u16* gatep, int gstride, u16* outp, int ostride, char* lds, int tid) {
;     ...
; #pragma unroll
;       for (int dt = 0; dt < 4; ++dt) {
;         const char* vp = vb + ((16 * dt + jn) * VROW + kk * 32 + 4 * q) * 2;
;         const uint2 lo = *reinterpret_cast<const uint2*>(vp), hi = *reinterpret_cast<const uint2*>(vp + 32);
;         uint4 w; w.x = lo.x; w.y = lo.y; w.z = hi.x; w.w = hi.y;
;         const bf16x8 vf = __builtin_bit_cast(bf16x8, w);
; #pragma unroll
;         for (int c = 0; c < NC; ++c) o[dt][c] = mfma16(vf, pf[c], o[dt][c]);
;       }
;     }
	v_mfma_f32_16x16x32_bf16 v[102:105], v[180:183], v[114:117], v[102:105]
	v_add_u32_e32 v169, 0x7800, v175
	v_add_u32_e32 v179, 0x8000, v175
	v_mfma_f32_16x16x32_bf16 v[86:89], v[180:183], v[106:109], v[86:89]
	v_mfma_f32_16x16x32_bf16 v[38:41], v[180:183], v[110:113], v[38:41]
	ds_read_b128 v[180:183], v168 offset:1280
	s_waitcnt lgkmcnt(0)
	v_mfma_f32_16x16x32_bf16 v[98:101], v[180:183], v[114:117], v[98:101]
	v_mfma_f32_16x16x32_bf16 v[82:85], v[180:183], v[106:109], v[82:85]
	v_mfma_f32_16x16x32_bf16 v[34:37], v[180:183], v[110:113], v[34:37]
	ds_read_b128 v[180:183], v169 offset:1536
	s_waitcnt lgkmcnt(0)
	v_mfma_f32_16x16x32_bf16 v[94:97], v[180:183], v[114:117], v[94:97]
	v_mfma_f32_16x16x32_bf16 v[78:81], v[180:183], v[106:109], v[78:81]
	v_mfma_f32_16x16x32_bf16 v[6:9], v[180:183], v[110:113], v[6:9]
	ds_read_b128 v[180:183], v179 offset:1792
	s_waitcnt lgkmcnt(0)
	v_mfma_f32_16x16x32_bf16 v[90:93], v[180:183], v[114:117], v[90:93]
	v_cvt_pk_bf16_f32 v114, v141, v143
	v_cvt_pk_bf16_f32 v115, v145, v147
	v_cvt_pk_bf16_f32 v116, v149, v151
	v_mfma_f32_16x16x32_bf16 v[74:77], v[180:183], v[106:109], v[74:77]
	v_cvt_pk_bf16_f32 v106, v140, v142
	ds_read_b128 v[140:143], v0 offset:1088
	v_cvt_pk_bf16_f32 v117, v153, v155
	v_mfma_f32_16x16x32_bf16 v[2:5], v[180:183], v[110:113], v[2:5]
	v_cvt_pk_bf16_f32 v110, v160, v161
	v_cvt_pk_bf16_f32 v111, v176, v177
	v_cvt_pk_bf16_f32 v112, v178, v208
	v_cvt_pk_bf16_f32 v113, v209, v210
	v_cvt_pk_bf16_f32 v107, v144, v146
	v_cvt_pk_bf16_f32 v108, v148, v150
	v_cvt_pk_bf16_f32 v109, v152, v154
	s_waitcnt lgkmcnt(0)
	v_mfma_f32_16x16x32_bf16 v[102:105], v[140:143], v[110:113], v[102:105]
	v_mfma_f32_16x16x32_bf16 v[86:89], v[140:143], v[114:117], v[86:89]
	v_mfma_f32_16x16x32_bf16 v[38:41], v[140:143], v[106:109], v[38:41]
	ds_read_b128 v[140:143], v168 offset:1344
	s_waitcnt lgkmcnt(0)
	v_mfma_f32_16x16x32_bf16 v[98:101], v[140:143], v[110:113], v[98:101]
	v_mfma_f32_16x16x32_bf16 v[82:85], v[140:143], v[114:117], v[82:85]
	v_mfma_f32_16x16x32_bf16 v[34:37], v[140:143], v[106:109], v[34:37]
	ds_read_b128 v[140:143], v169 offset:1600
	s_waitcnt lgkmcnt(0)
	v_mfma_f32_16x16x32_bf16 v[94:97], v[140:143], v[110:113], v[94:97]
	v_mfma_f32_16x16x32_bf16 v[78:81], v[140:143], v[114:117], v[78:81]
	v_mfma_f32_16x16x32_bf16 v[6:9], v[140:143], v[106:109], v[6:9]
	ds_read_b128 v[140:143], v179 offset:1856
	s_waitcnt lgkmcnt(0)
	v_mfma_f32_16x16x32_bf16 v[90:93], v[140:143], v[110:113], v[90:93]
	v_mov_b32_e32 v110, v159
	v_mfma_f32_16x16x32_bf16 v[74:77], v[140:143], v[114:117], v[74:77]
	v_mfma_f32_16x16x32_bf16 v[2:5], v[140:143], v[106:109], v[2:5]
	s_andn2_b64 vcc, exec, s[50:51]
	s_cbranch_vccz .LBB0_825
	s_branch .LBB0_826

; #define A_STORE(P, buf) { *reinterpret_cast<uint4*>(ks0 + (buf) * BUF_BYTES) = P##k0; *reinterpret_cast<uint4*>(ks1 + (buf) * BUF_BYTES) = P##k1; \
;     if (NKC == 3) *reinterpret_cast<uint4*>(ks2 + (buf) * BUF_BYTES) = P##k2;                                        \
;     *reinterpret_cast<uint4*>(vs0 + (buf) * BUF_BYTES) = P##v0; *reinterpret_cast<uint4*>(vs1 + (buf) * BUF_BYTES) = P##v1; }
; template <int KS, bool MASK, int NC, bool SH>
; DI void attn_block(const u16* Qp, int qstride, const u16* Kp, int kstride, const u16* Vtp, const u64* maskp, int nkt_w, int nkt_max,
;                    const u16* gatep, int gstride, u16* outp, int ostride, char* lds, int tid) {
;     ...
;     if (more) A_STORE(x, 0);
.LBB0_825:
	ds_write_b128 v164, v[42:45]
	ds_write_b128 v165, v[50:53]
	ds_write2_b64 v242, v[54:55], v[56:57] offset1:2
	ds_write2_b64 v244, v[62:63], v[64:65] offset1:2
